# attention main loop: K-tile LDS-DMA issue moved into the wait states after the first QK^T chain (was s_nop 11)
# speedup vs baseline: 1.0088x; 1.0068x over previous
.LBB0_429:
	s_mov_b32 s46, s75
	s_mov_b32 s47, s74
	s_mov_b32 s49, s51
	v_lshl_add_u32 v0, s48, 1, v218
	s_lshl_b32 s48, s76, 1
	v_add_u32_e32 v14, s48, v228
	ds_read_b128 v[2:5], v14 offset:4096
	ds_read_b128 v[6:9], v14 offset:6144
	ds_read_b64_tr_b16 v[10:11], v0
	ds_read_b64_tr_b16 v[12:13], v0 offset:512
	s_waitcnt lgkmcnt(5)
	v_mfma_f32_32x32x16_bf16 v[92:107], v[156:159], v[120:123], 0
	ds_read_b128 v[80:83], v14 offset:512
	ds_read_b128 v[156:159], v14 offset:2560
	ds_read_b64_tr_b16 v[164:165], v0 offset:4096
	ds_read_b64_tr_b16 v[166:167], v0 offset:4608
	s_waitcnt lgkmcnt(8)
	v_mfma_f32_32x32x16_bf16 v[92:107], v[160:163], v[116:119], v[92:107]
	ds_read_b128 v[160:163], v14 offset:4608
	ds_read_b128 v[168:171], v14 offset:6656
	ds_read_b64_tr_b16 v[172:173], v0 offset:1024
	ds_read_b64_tr_b16 v[174:175], v0 offset:1536
	s_waitcnt lgkmcnt(11)
	v_mfma_f32_32x32x16_bf16 v[92:107], v[2:5], v[112:115], v[92:107]
	ds_read_b64_tr_b16 v[2:3], v0 offset:5120
	ds_read_b64_tr_b16 v[4:5], v0 offset:5632
	s_waitcnt lgkmcnt(12)
	v_mfma_f32_32x32x16_bf16 v[92:107], v[6:9], v[108:111], v[92:107]
	s_add_u32 s74, s44, 0xff020000
	s_addc_u32 s75, s45, -1
	s_lshl_b32 s51, s77, 1
	s_add_i32 s51, s51, s72
	s_mov_b32 s76, m0
	s_mov_b32 m0, s51
	s_nop 0
	global_load_lds_dwordx4 v226, s[74:75]
	s_mov_b32 m0, s76
	s_add_u32 s74, s44, 0xff020080
	s_addc_u32 s75, s45, -1
	s_addk_i32 s51, 0x2000
	s_mov_b32 s76, m0
	s_mov_b32 m0, s51
	s_nop 0
	global_load_lds_dwordx4 v226, s[74:75]
	s_mov_b32 m0, s76
	v_exp_f32_e32 v14, v92
	v_exp_f32_e32 v15, v93
	v_exp_f32_e32 v124, v94
	v_exp_f32_e32 v128, v95
	s_waitcnt lgkmcnt(9)
	v_mfma_f32_32x32x16_bf16 v[80:95], v[80:83], v[120:123], 0
	ds_read_b64_tr_b16 v[6:7], v0 offset:2048
	ds_read_b64_tr_b16 v[8:9], v0 offset:2560
	v_add_f32_e32 v132, 0, v14
	v_add_f32_e32 v132, v15, v132
	v_add_f32_e32 v132, v124, v132
	v_add_f32_e32 v132, v128, v132
	v_cvt_pk_bf16_f32 v136, v14, v15
	v_cvt_pk_bf16_f32 v137, v124, v128
	v_exp_f32_e32 v14, v96
	v_exp_f32_e32 v15, v97
	v_exp_f32_e32 v124, v98
	s_waitcnt lgkmcnt(10)
	v_mfma_f32_32x32x16_bf16 v[80:95], v[156:159], v[116:119], v[80:95]
	v_exp_f32_e32 v128, v99
	ds_read_b64_tr_b16 v[96:97], v0 offset:6144
	ds_read_b64_tr_b16 v[98:99], v0 offset:6656
	v_add_f32_e32 v132, v14, v132
	v_add_f32_e32 v132, v15, v132
	v_add_f32_e32 v132, v124, v132
	v_add_f32_e32 v132, v128, v132
	v_cvt_pk_bf16_f32 v138, v14, v15
	v_cvt_pk_bf16_f32 v139, v124, v128
	v_exp_f32_e32 v14, v100
	v_exp_f32_e32 v15, v101
	v_exp_f32_e32 v124, v102
	s_waitcnt lgkmcnt(9)
	v_mfma_f32_32x32x16_bf16 v[80:95], v[160:163], v[112:115], v[80:95]
	v_exp_f32_e32 v128, v103
	ds_read_b64_tr_b16 v[100:101], v0 offset:3072
	ds_read_b64_tr_b16 v[102:103], v0 offset:3584
	v_add_f32_e32 v132, v14, v132
	v_add_f32_e32 v132, v15, v132
	v_add_f32_e32 v132, v124, v132
	v_add_f32_e32 v156, v128, v132
	v_cvt_pk_bf16_f32 v132, v14, v15
	v_cvt_pk_bf16_f32 v133, v124, v128
	v_exp_f32_e32 v14, v104
	v_exp_f32_e32 v15, v105
	v_exp_f32_e32 v124, v106
	s_waitcnt lgkmcnt(10)
	v_mfma_f32_32x32x16_bf16 v[80:95], v[168:171], v[108:111], v[80:95]
	v_exp_f32_e32 v128, v107
	ds_read_b64_tr_b16 v[104:105], v0 offset:7168
	ds_read_b64_tr_b16 v[106:107], v0 offset:7680
	v_add_f32_e32 v134, v14, v156
	v_add_f32_e32 v134, v15, v134
	v_add_f32_e32 v134, v124, v134
	v_add_f32_e32 v156, v128, v134
	v_cvt_pk_bf16_f32 v134, v14, v15
	v_cvt_pk_bf16_f32 v135, v124, v128
	s_add_u32 s74, s44, 0xfffe0000
	s_addc_u32 s75, s45, -1
	s_lshl_b32 s51, s47, 1
	s_add_i32 s51, s51, s73
	s_mov_b32 s76, m0
	s_mov_b32 m0, s51
	s_nop 0
	global_load_lds_dwordx4 v227, s[74:75]
	s_mov_b32 m0, s76
	s_add_u32 s74, s44, 0xfffe0080
	s_addc_u32 s75, s45, -1
	s_addk_i32 s51, 0x2000
	s_mov_b32 s76, m0
	s_mov_b32 m0, s51
	s_nop 0
	global_load_lds_dwordx4 v227, s[74:75]
	s_mov_b32 m0, s76
	v_mfma_f32_32x32x16_bf16 v[16:31], v[152:155], v[10:13], v[16:31]
	v_exp_f32_e32 v14, v80
	ds_read_b64_tr_b16 v[10:11], v0 offset:8192
	ds_read_b64_tr_b16 v[12:13], v0 offset:8704
	v_exp_f32_e32 v15, v81
	v_mov_b32_e32 v80, v14
	v_add_f32_e32 v14, v14, v156
	s_nop 0
	v_cvt_pk_bf16_f32 v128, v80, v15
	v_mfma_f32_32x32x16_bf16 v[32:47], v[152:155], v[164:167], v[32:47]
	ds_read_b64_tr_b16 v[156:157], v0 offset:12288
	ds_read_b64_tr_b16 v[158:159], v0 offset:12800
	v_add_f32_e32 v14, v15, v14
	s_waitcnt lgkmcnt(14)
	v_mfma_f32_32x32x16_bf16 v[16:31], v[148:151], v[172:175], v[16:31]
	v_exp_f32_e32 v15, v82
	ds_read_b64_tr_b16 v[160:161], v0 offset:9216
	ds_read_b64_tr_b16 v[162:163], v0 offset:9728
	v_add_f32_e32 v14, v15, v14
	s_waitcnt lgkmcnt(14)
	v_mfma_f32_32x32x16_bf16 v[32:47], v[148:151], v[2:5], v[32:47]
	v_exp_f32_e32 v80, v83
	ds_read_b64_tr_b16 v[2:3], v0 offset:13312
	ds_read_b64_tr_b16 v[4:5], v0 offset:13824
	v_add_f32_e32 v14, v80, v14
	v_cvt_pk_bf16_f32 v129, v15, v80
	s_waitcnt lgkmcnt(14)
	v_mfma_f32_32x32x16_bf16 v[16:31], v[144:147], v[6:9], v[16:31]
	v_exp_f32_e32 v15, v84
	ds_read_b64_tr_b16 v[6:7], v0 offset:10240
	ds_read_b64_tr_b16 v[8:9], v0 offset:10752
	v_add_f32_e32 v14, v15, v14
	s_waitcnt lgkmcnt(14)
	v_mfma_f32_32x32x16_bf16 v[32:47], v[144:147], v[96:99], v[32:47]
	v_exp_f32_e32 v84, v85
	ds_read_b64_tr_b16 v[80:81], v0 offset:14336
	ds_read_b64_tr_b16 v[82:83], v0 offset:14848
	v_add_f32_e32 v14, v84, v14
	v_cvt_pk_bf16_f32 v130, v15, v84
	s_waitcnt lgkmcnt(14)
	v_mfma_f32_32x32x16_bf16 v[16:31], v[140:143], v[100:103], v[16:31]
	v_exp_f32_e32 v15, v86
	ds_read_b64_tr_b16 v[96:97], v0 offset:11264
	ds_read_b64_tr_b16 v[98:99], v0 offset:11776
	v_add_f32_e32 v14, v15, v14
	s_waitcnt lgkmcnt(14)
	v_mfma_f32_32x32x16_bf16 v[32:47], v[140:143], v[104:107], v[32:47]
	v_exp_f32_e32 v100, v87
	ds_read_b64_tr_b16 v[84:85], v0 offset:15360
	ds_read_b64_tr_b16 v[86:87], v0 offset:15872
	v_add_f32_e32 v0, v100, v14
	v_cvt_pk_bf16_f32 v131, v15, v100
	v_exp_f32_e32 v14, v88
	v_exp_f32_e32 v15, v89
	s_waitcnt lgkmcnt(14)
	v_mfma_f32_32x32x16_bf16 v[48:63], v[152:155], v[10:13], v[48:63]
	v_lshl_add_u32 v88, s46, 1, v228
	v_mov_b32_e32 v89, v14
	v_add_f32_e32 v0, v14, v0
	s_nop 0
	v_cvt_pk_bf16_f32 v124, v89, v15
	s_waitcnt lgkmcnt(12)
	v_mfma_f32_32x32x16_bf16 v[64:79], v[152:155], v[156:159], v[64:79]
	v_add_f32_e32 v0, v15, v0
	v_exp_f32_e32 v10, v90
	s_waitcnt lgkmcnt(10)
	v_mfma_f32_32x32x16_bf16 v[48:63], v[148:151], v[160:163], v[48:63]
	v_add_f32_e32 v0, v10, v0
	v_exp_f32_e32 v11, v91
	s_waitcnt lgkmcnt(8)
	v_mfma_f32_32x32x16_bf16 v[64:79], v[148:151], v[2:5], v[64:79]
	v_add_f32_e32 v0, v11, v0
	v_cvt_pk_bf16_f32 v125, v10, v11
	v_exp_f32_e32 v10, v92
	s_waitcnt lgkmcnt(6)
	v_mfma_f32_32x32x16_bf16 v[48:63], v[144:147], v[6:9], v[48:63]
	v_add_f32_e32 v0, v10, v0
	v_exp_f32_e32 v6, v93
	s_waitcnt lgkmcnt(4)
	v_mfma_f32_32x32x16_bf16 v[64:79], v[144:147], v[80:83], v[64:79]
	ds_read_b128 v[2:5], v88
	v_add_f32_e32 v0, v6, v0
	v_cvt_pk_bf16_f32 v126, v10, v6
	v_exp_f32_e32 v10, v94
	s_waitcnt lgkmcnt(3)
	v_mfma_f32_32x32x16_bf16 v[48:63], v[140:143], v[96:99], v[48:63]
	v_add_f32_e32 v0, v10, v0
	v_exp_f32_e32 v11, v95
	s_waitcnt lgkmcnt(1)
	v_mfma_f32_32x32x16_bf16 v[64:79], v[140:143], v[84:87], v[64:79]
	ds_read_b128 v[6:9], v88 offset:2048
	v_add_f32_e32 v0, v11, v0
	v_cvt_pk_bf16_f32 v127, v10, v11
	s_add_i32 s51, s47, 0x2000
	s_cmpk_lg_i32 s47, 0x4000
	s_waitcnt vmcnt(4) lgkmcnt(0)
	s_barrier
	s_cselect_b32 s51, s51, 0
	s_add_i32 s74, s46, 0x2000
	s_cmpk_lg_i32 s46, 0x6000
	s_cselect_b32 s76, s74, 0
	v_add_f32_e32 v0, v229, v0
	v_lshl_add_u32 v14, s49, 1, v218
	ds_read_b128 v[10:13], v88 offset:4096
	ds_read_b128 v[80:83], v88 offset:6144
	ds_read_b64_tr_b16 v[156:157], v14
	ds_read_b64_tr_b16 v[158:159], v14 offset:512
	v_lshl_add_u32 v15, s76, 1, v228
	s_waitcnt lgkmcnt(5)
	v_mfma_f32_32x32x16_bf16 v[92:107], v[2:5], v[120:123], 0
	ds_read_b128 v[2:5], v88 offset:512
	ds_read_b128 v[160:163], v88 offset:2560
	ds_read_b64_tr_b16 v[164:165], v14 offset:4096
	ds_read_b64_tr_b16 v[166:167], v14 offset:4608
	s_waitcnt lgkmcnt(8)
	v_mfma_f32_32x32x16_bf16 v[92:107], v[6:9], v[116:119], v[92:107]
	ds_read_b128 v[6:9], v88 offset:4608
	ds_read_b128 v[168:171], v88 offset:6656
	ds_read_b64_tr_b16 v[172:173], v14 offset:1024
	ds_read_b64_tr_b16 v[174:175], v14 offset:1536
	s_waitcnt lgkmcnt(11)
	v_mfma_f32_32x32x16_bf16 v[92:107], v[10:13], v[112:115], v[92:107]
	ds_read_b64_tr_b16 v[10:11], v14 offset:5120
	ds_read_b64_tr_b16 v[12:13], v14 offset:5632
	s_waitcnt lgkmcnt(12)
	v_mfma_f32_32x32x16_bf16 v[92:107], v[80:83], v[108:111], v[92:107]
	s_add_u32 s74, s44, 0xff040000
	s_addc_u32 s75, s45, -1
	s_add_i32 s77, s48, s72
	s_mov_b32 s48, m0
	s_mov_b32 m0, s77
	s_nop 0
	global_load_lds_dwordx4 v226, s[74:75]
	s_mov_b32 m0, s48
	s_add_u32 s48, s44, 0xff040080
	s_addc_u32 s49, s45, -1
	s_add_i32 s74, s77, 0x2000
	s_mov_b32 s75, m0
	s_mov_b32 m0, s74
	s_nop 0
	global_load_lds_dwordx4 v226, s[48:49]
	s_mov_b32 m0, s75
	v_exp_f32_e32 v140, v92
	v_exp_f32_e32 v144, v93
	v_exp_f32_e32 v148, v94
	v_exp_f32_e32 v149, v95
	s_waitcnt lgkmcnt(9)
	v_mfma_f32_32x32x16_bf16 v[80:95], v[2:5], v[120:123], 0
	ds_read_b64_tr_b16 v[2:3], v14 offset:2048
	ds_read_b64_tr_b16 v[4:5], v14 offset:2560
	v_add_f32_e32 v152, 0, v140
	v_add_f32_e32 v152, v144, v152
	v_add_f32_e32 v152, v148, v152
	v_add_f32_e32 v176, v149, v152
	v_cvt_pk_bf16_f32 v152, v140, v144
	v_cvt_pk_bf16_f32 v153, v148, v149
	v_exp_f32_e32 v140, v96
	v_exp_f32_e32 v144, v97
	v_exp_f32_e32 v148, v98
	s_waitcnt lgkmcnt(10)
	v_mfma_f32_32x32x16_bf16 v[80:95], v[160:163], v[116:119], v[80:95]
	v_exp_f32_e32 v149, v99
	ds_read_b64_tr_b16 v[96:97], v14 offset:6144
	ds_read_b64_tr_b16 v[98:99], v14 offset:6656
	v_add_f32_e32 v154, v140, v176
	v_add_f32_e32 v154, v144, v154
	v_add_f32_e32 v154, v148, v154
	v_add_f32_e32 v160, v149, v154
	v_cvt_pk_bf16_f32 v154, v140, v144
	v_cvt_pk_bf16_f32 v155, v148, v149
	v_exp_f32_e32 v100, v100
	v_exp_f32_e32 v101, v101
	v_exp_f32_e32 v102, v102
	s_waitcnt lgkmcnt(9)
	v_mfma_f32_32x32x16_bf16 v[80:95], v[6:9], v[112:115], v[80:95]
	v_exp_f32_e32 v103, v103
	ds_read_b64_tr_b16 v[6:7], v14 offset:3072
	ds_read_b64_tr_b16 v[8:9], v14 offset:3584
	v_add_f32_e32 v140, v100, v160
	v_add_f32_e32 v140, v101, v140
	v_add_f32_e32 v140, v102, v140
	v_add_f32_e32 v140, v103, v140
	v_cvt_pk_bf16_f32 v148, v100, v101
	v_cvt_pk_bf16_f32 v149, v102, v103
	v_exp_f32_e32 v104, v104
	v_exp_f32_e32 v105, v105
	v_exp_f32_e32 v106, v106
	s_waitcnt lgkmcnt(10)
	v_mfma_f32_32x32x16_bf16 v[80:95], v[168:171], v[108:111], v[80:95]
	v_exp_f32_e32 v107, v107
	ds_read_b64_tr_b16 v[100:101], v14 offset:7168
	ds_read_b64_tr_b16 v[102:103], v14 offset:7680
	v_add_f32_e32 v140, v104, v140
	v_add_f32_e32 v140, v105, v140
	v_add_f32_e32 v140, v106, v140
	v_add_f32_e32 v140, v107, v140
	v_cvt_pk_bf16_f32 v150, v104, v105
	v_cvt_pk_bf16_f32 v151, v106, v107
	s_lshl_b32 s48, s51, 1
	s_add_i32 s42, s42, 2
	s_add_i32 s74, s48, s73
	s_mov_b32 s48, m0
	s_mov_b32 m0, s74
	s_nop 0
	global_load_lds_dwordx4 v227, s[44:45]
	s_mov_b32 m0, s48
	s_add_u32 s48, s44, 0x80
	s_addc_u32 s49, s45, 0
	s_addk_i32 s74, 0x2000
	s_mov_b32 s75, m0
	s_mov_b32 m0, s74
	s_nop 0
	global_load_lds_dwordx4 v227, s[48:49]
	s_mov_b32 m0, s75
	v_mfma_f32_32x32x16_bf16 v[16:31], v[136:139], v[156:159], v[16:31]
	v_exp_f32_e32 v80, v80
	ds_read_b64_tr_b16 v[104:105], v14 offset:8192
	ds_read_b64_tr_b16 v[106:107], v14 offset:8704
	v_add_f32_e32 v140, v80, v140
	v_mfma_f32_32x32x16_bf16 v[32:47], v[136:139], v[164:167], v[32:47]
	v_exp_f32_e32 v81, v81
	ds_read_b64_tr_b16 v[156:157], v14 offset:12288
	ds_read_b64_tr_b16 v[158:159], v14 offset:12800
	v_add_f32_e32 v140, v81, v140
	v_cvt_pk_bf16_f32 v144, v80, v81
	s_waitcnt lgkmcnt(14)
	v_mfma_f32_32x32x16_bf16 v[16:31], v[132:135], v[172:175], v[16:31]
	v_exp_f32_e32 v80, v82
	ds_read_b64_tr_b16 v[160:161], v14 offset:9216
	ds_read_b64_tr_b16 v[162:163], v14 offset:9728
	v_add_f32_e32 v81, v80, v140
	s_waitcnt lgkmcnt(14)
	v_mfma_f32_32x32x16_bf16 v[32:47], v[132:135], v[10:13], v[32:47]
	v_exp_f32_e32 v82, v83
	ds_read_b64_tr_b16 v[10:11], v14 offset:13312
	ds_read_b64_tr_b16 v[12:13], v14 offset:13824
	v_add_f32_e32 v81, v82, v81
	v_cvt_pk_bf16_f32 v145, v80, v82
	s_waitcnt lgkmcnt(14)
	v_mfma_f32_32x32x16_bf16 v[16:31], v[128:131], v[2:5], v[16:31]
	v_exp_f32_e32 v84, v84
	ds_read_b64_tr_b16 v[2:3], v14 offset:10240
	ds_read_b64_tr_b16 v[4:5], v14 offset:10752
	v_add_f32_e32 v140, v84, v81
	s_waitcnt lgkmcnt(14)
	v_mfma_f32_32x32x16_bf16 v[32:47], v[128:131], v[96:99], v[32:47]
	v_exp_f32_e32 v85, v85
	ds_read_b64_tr_b16 v[80:81], v14 offset:14336
	ds_read_b64_tr_b16 v[82:83], v14 offset:14848
	v_add_f32_e32 v96, v85, v140
	v_cvt_pk_bf16_f32 v146, v84, v85
	s_waitcnt lgkmcnt(14)
	v_mfma_f32_32x32x16_bf16 v[16:31], v[124:127], v[6:9], v[16:31]
	v_exp_f32_e32 v97, v86
	ds_read_b64_tr_b16 v[6:7], v14 offset:11264
	ds_read_b64_tr_b16 v[8:9], v14 offset:11776
	v_add_f32_e32 v96, v97, v96
	s_waitcnt lgkmcnt(14)
	v_mfma_f32_32x32x16_bf16 v[32:47], v[124:127], v[100:103], v[32:47]
	v_exp_f32_e32 v98, v87
	ds_read_b64_tr_b16 v[84:85], v14 offset:15360
	ds_read_b64_tr_b16 v[86:87], v14 offset:15872
	v_add_f32_e32 v14, v98, v96
	v_cvt_pk_bf16_f32 v147, v97, v98
	v_exp_f32_e32 v88, v88
	s_waitcnt lgkmcnt(14)
	v_mfma_f32_32x32x16_bf16 v[48:63], v[136:139], v[104:107], v[48:63]
	v_add_f32_e32 v14, v88, v14
	v_exp_f32_e32 v89, v89
	s_waitcnt lgkmcnt(12)
	v_mfma_f32_32x32x16_bf16 v[64:79], v[136:139], v[156:159], v[64:79]
	v_add_f32_e32 v14, v89, v14
	v_cvt_pk_bf16_f32 v140, v88, v89
	v_exp_f32_e32 v88, v90
	s_waitcnt lgkmcnt(10)
	v_mfma_f32_32x32x16_bf16 v[48:63], v[132:135], v[160:163], v[48:63]
	v_add_f32_e32 v14, v88, v14
	v_exp_f32_e32 v89, v91
	s_waitcnt lgkmcnt(8)
	v_mfma_f32_32x32x16_bf16 v[64:79], v[132:135], v[10:13], v[64:79]
	v_add_f32_e32 v14, v89, v14
	v_cvt_pk_bf16_f32 v141, v88, v89
	v_exp_f32_e32 v10, v92
	s_waitcnt lgkmcnt(6)
	v_mfma_f32_32x32x16_bf16 v[48:63], v[128:131], v[2:5], v[48:63]
	v_add_f32_e32 v2, v10, v14
	s_waitcnt lgkmcnt(4)
	v_mfma_f32_32x32x16_bf16 v[64:79], v[128:131], v[80:83], v[64:79]
	v_exp_f32_e32 v3, v93
	ds_read_b128 v[156:159], v15
	v_add_f32_e32 v2, v3, v2
	v_cvt_pk_bf16_f32 v142, v10, v3
	v_exp_f32_e32 v3, v94
	s_waitcnt lgkmcnt(3)
	v_mfma_f32_32x32x16_bf16 v[48:63], v[124:127], v[6:9], v[48:63]
	v_add_f32_e32 v2, v3, v2
	s_waitcnt lgkmcnt(1)
	v_mfma_f32_32x32x16_bf16 v[64:79], v[124:127], v[84:87], v[64:79]
	v_exp_f32_e32 v4, v95
	ds_read_b128 v[160:163], v15 offset:2048
	v_add_f32_e32 v2, v4, v2
	v_cvt_pk_bf16_f32 v143, v3, v4
	s_add_i32 s48, s51, 0x2000
	s_cmpk_lg_i32 s51, 0x4000
	s_cselect_b32 s74, s48, 0
	s_add_i32 s48, s76, 0x2000
	s_cmpk_lg_i32 s76, 0x6000
	s_waitcnt vmcnt(4) lgkmcnt(0)
	s_barrier
	s_cselect_b32 s75, s48, 0
	s_add_u32 s44, s44, 0x40000
	s_addc_u32 s45, s45, 0
	v_add_f32_e32 v229, v0, v2
	s_cmp_ge_i32 s42, s43
	s_mov_b32 s48, s47
	s_mov_b32 s77, s46
	s_cbranch_scc0 .LBB0_429
	s_add_i32 s43, s42, 1
	s_cmp_lt_i32 s43, s50
	s_mov_b64 s[44:45], -1
	s_cbranch_scc1 .LBB0_432
